# attention K/V LDS-DMA: SGPR base + 32-bit per-lane offsets (3 v_add_u32 + 2 SALU per tile instead of 5 64-bit VALU adds), on top of dynamic pass3
# speedup vs baseline: 1.0146x; 1.0019x over previous
; __device__ __forceinline__ int opaque_tid() { int t = threadIdx.x; asm volatile("" : "+v"(t)); return t; }
; __device__ __forceinline__ int v_st(int k, int c) { const int kk = (k & ~0xC) | ((k & 4) << 1) | ((k & 8) >> 1); return ((kk >> 3) * 4 + (c >> 5)) * 512 + ((kk & 7) * 32 + (c & 31)) * 2; }
; __device__ __forceinline__ int v_rd_base(int lane) { return ((lane & 3) << 3) | (((lane >> 2) & 3) << 6) | (((lane >> 4) & 1) << 5) | (((lane >> 5) & 1) << 8); }
; __device__ __forceinline__ void attn_unit(const bf16_t* __restrict__ Qb, const bf16_t* __restrict__ Kn, const bf16_t* __restrict__ Kr, const bf16_t* __restrict__ Vh,
;                                           bf16_t* __restrict__ Ob, char* lds) {
;   const int tid = opaque_tid(), wid = tid >> 6, lane = tid & 63, r32 = lane & 31, hi = lane >> 5;
;   char* V_lds = lds; char* K_lds = lds + 2 * SHM_V;
;   float* ws = (float*)(lds + 2 * SHM_V + 2 * SHM_K) + wid * 64; float* li_l = ws; float* al_l = ws + 32;
;   float m_reg = 0.f, l_reg = 0; f32x16 o[4] = {}; bf16x8 qr[8];
;   char* qL = lds + 2 * SHM_V + 2 * SHM_K + 2048 + wid * 4096 + lane * 16;
;   const bf16_t* Qw = Qb + (long)(wid * 32 + r32) * 192 + hi * 8;
; #pragma unroll
;   for (int d0 = 0; d0 < 8; ++d0) qr[d0] = *reinterpret_cast<const bf16x8*>(Qw + d0 * 16);
; #pragma unroll
;   for (int d0 = 8; d0 < 12; ++d0) *reinterpret_cast<bf16x8*>(qL + (d0 - 8) * 1024) = *reinterpret_cast<const bf16x8*>(Qw + d0 * 16);
;   const int sr = tid >> 4, sc = (tid & 15) * 8, vst0 = v_st(sr, sc), vst1 = v_st(32 + sr, sc);
;   const int rr = tid >> 3, rc = (tid & 7) * 8;
;   const int kst0 = KSWZ(sr, sc * 2), kst1 = KSWZ(32 + sr, sc * 2), kst2 = KSWZ(rr, 256 + rc * 2);
;   const int vb0 = (int)(uintptr_t)V_lds + v_rd_base(lane);
;   struct { bf16x8 vs0, vs1, ks0, ks1, ks2; } sr_[SDEPTH];
;     ...
;   f32x16 pA0, pA1, pB0, pB1; float alA, alB; bf16x8 pa0, pa1, pa2, pa3; const int NT = T / KVBLK;
;   constexpr int SE = 0, SO = SDEPTH - 1;
;   SLOAD(SE, 0); asm volatile("s_waitcnt vmcnt(0)" ::: "memory"); SWRITE(0, SE); __syncthreads();
;   qkt(pA0, pA1, K_lds, qr, qL, r32, hi, 0.f); partialSM<true>(pA0, pA1, m_reg, alA);
;   SLOAD(SO, KVBLK); if constexpr (SDEPTH == 2) { if (2 < NT) SLOAD(SE, 2 * KVBLK); }
.LBB0_465:
.LBB0_466:
	s_mul_i32 s41, s16, 0x18000
	s_mul_hi_u32 s42, s16, 0x18000
	s_add_u32 s20, s68, s28
	s_addc_u32 s21, s69, s5
	s_add_u32 s20, s20, s41
	s_addc_u32 s21, s21, s42
	s_add_u32 s20, s20, 0x23300000
	s_addc_u32 s21, s21, 0
	s_add_u32 s24, s68, s14
	s_addc_u32 s25, s69, s15
	s_add_u32 s26, s24, 0x2d300000
	s_addc_u32 s27, s25, 0
	s_add_u32 s24, s24, 0x29300000
	s_addc_u32 s25, s25, 0
	s_add_u32 s30, s68, s8
	s_addc_u32 s31, s69, s9
	s_add_u32 s30, s30, 0x31300000
	s_addc_u32 s31, s31, 0
	s_lshl_b32 s41, s16, 20
	s_add_u32 s36, s68, s10
	s_addc_u32 s37, s69, s11
	s_add_u32 s36, s36, s41
	s_addc_u32 s37, s37, 0
	s_add_u32 s36, s36, s29
	s_addc_u32 s37, s37, 0
	s_add_u32 s36, s36, 0x6300800
	s_addc_u32 s37, s37, 0
	s_mov_b32 s38, 0x4138aa3b
	s_mov_b32 s22, 0x4000
	s_mov_b32 s23, 0
	v_and_b32_e32 v234, 63, v195
	v_lshrrev_b32_e32 v235, 6, v195
	v_and_b32_e32 v243, 15, v234
	v_readfirstlane_b32 s40, v235
	v_lshrrev_b32_e32 v244, 4, v234
	s_mul_i32 s41, s40, 0x3000
	s_add_u32 s20, s20, s41
	s_addc_u32 s21, s21, 0
	s_lshl_b32 s41, s40, 17
	s_add_u32 s36, s36, s41
	s_addc_u32 s37, s37, 0
	s_lshl_b32 s43, s40, 10
	v_mul_u32_u24_e32 v245, 0x180, v243
	v_lshl_add_u32 v245, v244, 4, v245
	v_add_u32_e32 v246, 0x1800, v245
	global_load_dwordx4 v[64:67], v245, s[20:21] offset:0
	global_load_dwordx4 v[68:71], v245, s[20:21] offset:64
	global_load_dwordx4 v[72:75], v245, s[20:21] offset:128
	global_load_dwordx4 v[76:79], v245, s[20:21] offset:192
	global_load_dwordx4 v[80:83], v245, s[20:21] offset:256
	global_load_dwordx4 v[84:87], v245, s[20:21] offset:320
	global_load_dwordx4 v[88:91], v246, s[20:21] offset:0
	global_load_dwordx4 v[92:95], v246, s[20:21] offset:64
	global_load_dwordx4 v[96:99], v246, s[20:21] offset:128
	global_load_dwordx4 v[100:103], v246, s[20:21] offset:192
	global_load_dwordx4 v[104:107], v246, s[20:21] offset:256
	global_load_dwordx4 v[108:111], v246, s[20:21] offset:320
	v_lshlrev_b32_e32 v247, 4, v234
	v_add_u32_e32 v247, s43, v247
	v_mov_b32_e32 v248, v247
	v_mul_u32_u24_e32 v249, 0xaaab, v248
	v_lshrrev_b32_e32 v249, 24, v249
	v_mul_u32_u24_e32 v250, 0x180, v249
	v_sub_u32_e32 v250, v248, v250
	v_lshrrev_b32_e32 v250, 4, v250
	v_and_b32_e32 v251, 7, v249
	v_xor_b32_e32 v196, v250, v251
	v_lshlrev_b32_e32 v196, 4, v196
	v_lshl_add_u32 v196, v249, 8, v196
	v_add_u32_e32 v197, -16, v250
	v_xor_b32_e32 v197, v197, v251
	v_lshlrev_b32_e32 v197, 4, v197
	v_lshl_add_u32 v197, v249, 7, v197
	v_cmp_le_u32_e64 s[34:35], 16, v250
	s_sub_u32 s42, s30, s24
	v_add_u32_e32 v197, s42, v197
	v_cndmask_b32_e64 v178, v196, v197, s[34:35]
	v_mov_b32_e32 v198, 0x4000
	v_mov_b32_e32 v222, 0x2000
	v_cndmask_b32_e64 v188, v198, v222, s[34:35]
	v_mov_b32_e32 v189, 0
	v_add_u32_e32 v248, 8192, v247
	v_mul_u32_u24_e32 v249, 0xaaab, v248
	v_lshrrev_b32_e32 v249, 24, v249
	v_mul_u32_u24_e32 v250, 0x180, v249
	v_sub_u32_e32 v250, v248, v250
	v_lshrrev_b32_e32 v250, 4, v250
	v_and_b32_e32 v251, 7, v249
	v_xor_b32_e32 v196, v250, v251
	v_lshlrev_b32_e32 v196, 4, v196
	v_lshl_add_u32 v196, v249, 8, v196
	v_add_u32_e32 v197, -16, v250
	v_xor_b32_e32 v197, v197, v251
	v_lshlrev_b32_e32 v197, 4, v197
	v_lshl_add_u32 v197, v249, 7, v197
	v_cmp_le_u32_e64 s[34:35], 16, v250
	s_sub_u32 s42, s30, s24
	v_add_u32_e32 v197, s42, v197
	v_cndmask_b32_e64 v180, v196, v197, s[34:35]
	v_mov_b32_e32 v198, 0x4000
	v_mov_b32_e32 v222, 0x2000
	v_cndmask_b32_e64 v190, v198, v222, s[34:35]
	v_mov_b32_e32 v191, 0
	v_add_u32_e32 v248, 16384, v247
	v_mul_u32_u24_e32 v249, 0xaaab, v248
	v_lshrrev_b32_e32 v249, 24, v249
	v_mul_u32_u24_e32 v250, 0x180, v249
	v_sub_u32_e32 v250, v248, v250
	v_lshrrev_b32_e32 v250, 4, v250
	v_and_b32_e32 v251, 7, v249
	v_xor_b32_e32 v196, v250, v251
	v_lshlrev_b32_e32 v196, 4, v196
	v_lshl_add_u32 v196, v249, 8, v196
	v_add_u32_e32 v197, -16, v250
	v_xor_b32_e32 v197, v197, v251
	v_lshlrev_b32_e32 v197, 4, v197
	v_lshl_add_u32 v197, v249, 7, v197
	v_cmp_le_u32_e64 s[34:35], 16, v250
	s_sub_u32 s42, s30, s24
	v_add_u32_e32 v197, s42, v197
	v_cndmask_b32_e64 v182, v196, v197, s[34:35]
	v_mov_b32_e32 v198, 0x4000
	v_mov_b32_e32 v222, 0x2000
	v_cndmask_b32_e64 v192, v198, v222, s[34:35]
	v_mov_b32_e32 v193, 0
	v_mov_b32_e32 v248, v247
	v_lshrrev_b32_e32 v249, 8, v248
	v_and_b32_e32 v250, 7, v249
	v_bfe_u32 v251, v248, 5, 3
	v_xor_b32_e32 v251, v251, v250
	v_lshrrev_b32_e32 v196, 3, v249
	v_lshl_or_b32 v196, v196, 3, v251
	v_lshlrev_b32_e32 v196, 8, v196
	v_lshl_add_u32 v196, v250, 5, v196
	v_and_b32_e32 v251, 16, v248
	v_add_u32_e32 v196, v196, v251
	v_mov_b32_e32 v184, v196
	v_add_u32_e32 v248, 8192, v247
	v_lshrrev_b32_e32 v249, 8, v248
	v_and_b32_e32 v250, 7, v249
	v_bfe_u32 v251, v248, 5, 3
	v_xor_b32_e32 v251, v251, v250
	v_lshrrev_b32_e32 v196, 3, v249
	v_lshl_or_b32 v196, v196, 3, v251
	v_lshlrev_b32_e32 v196, 8, v196
	v_lshl_add_u32 v196, v250, 5, v196
	v_and_b32_e32 v251, 16, v248
	v_add_u32_e32 v196, v196, v251
	v_mov_b32_e32 v186, v196
	s_add_i32 m0, s43, 49152
	s_nop 0
	global_load_lds_dwordx4 v178, s[24:25]
	s_add_i32 m0, s43, 57344
	s_nop 0
	global_load_lds_dwordx4 v180, s[24:25]
	s_add_i32 m0, s43, 65536
	s_nop 0
	global_load_lds_dwordx4 v182, s[24:25]
	s_add_i32 m0, s43, 0
	s_nop 0
	global_load_lds_dwordx4 v184, s[26:27]
	s_add_i32 m0, s43, 8192
	s_nop 0
	global_load_lds_dwordx4 v186, s[26:27]
	v_add_u32_e32 v178, v188, v178
	v_add_u32_e32 v180, v190, v180
	v_add_u32_e32 v182, v192, v182
	s_add_u32 s26, s26, 0x4000
	s_addc_u32 s27, s27, 0
	s_add_i32 m0, s43, 73728
	s_nop 0
	global_load_lds_dwordx4 v178, s[24:25]
	s_add_i32 m0, s43, 81920
	s_nop 0
	global_load_lds_dwordx4 v180, s[24:25]
	s_add_i32 m0, s43, 90112
	s_nop 0
; __device__ __forceinline__ int opaque_tid() { int t = threadIdx.x; asm volatile("" : "+v"(t)); return t; }
; __device__ __forceinline__ int v_st(int k, int c) { const int kk = (k & ~0xC) | ((k & 4) << 1) | ((k & 8) >> 1); return ((kk >> 3) * 4 + (c >> 5)) * 512 + ((kk & 7) * 32 + (c & 31)) * 2; }
; __device__ __forceinline__ int v_rd_base(int lane) { return ((lane & 3) << 3) | (((lane >> 2) & 3) << 6) | (((lane >> 4) & 1) << 5) | (((lane >> 5) & 1) << 8); }
; __device__ __forceinline__ void attn_unit(const bf16_t* __restrict__ Qb, const bf16_t* __restrict__ Kn, const bf16_t* __restrict__ Kr, const bf16_t* __restrict__ Vh,
;                                           bf16_t* __restrict__ Ob, char* lds) {
;   const int tid = opaque_tid(), wid = tid >> 6, lane = tid & 63, r32 = lane & 31, hi = lane >> 5;
;   char* V_lds = lds; char* K_lds = lds + 2 * SHM_V;
;   float* ws = (float*)(lds + 2 * SHM_V + 2 * SHM_K) + wid * 64; float* li_l = ws; float* al_l = ws + 32;
;   float m_reg = 0.f, l_reg = 0; f32x16 o[4] = {}; bf16x8 qr[8];
;   char* qL = lds + 2 * SHM_V + 2 * SHM_K + 2048 + wid * 4096 + lane * 16;
;   const bf16_t* Qw = Qb + (long)(wid * 32 + r32) * 192 + hi * 8;
; #pragma unroll
;   for (int d0 = 0; d0 < 8; ++d0) qr[d0] = *reinterpret_cast<const bf16x8*>(Qw + d0 * 16);
; #pragma unroll
;   for (int d0 = 8; d0 < 12; ++d0) *reinterpret_cast<bf16x8*>(qL + (d0 - 8) * 1024) = *reinterpret_cast<const bf16x8*>(Qw + d0 * 16);
;   const int sr = tid >> 4, sc = (tid & 15) * 8, vst0 = v_st(sr, sc), vst1 = v_st(32 + sr, sc);
;   const int rr = tid >> 3, rc = (tid & 7) * 8;
;   const int kst0 = KSWZ(sr, sc * 2), kst1 = KSWZ(32 + sr, sc * 2), kst2 = KSWZ(rr, 256 + rc * 2);
;   const int vb0 = (int)(uintptr_t)V_lds + v_rd_base(lane);
;   struct { bf16x8 vs0, vs1, ks0, ks1, ks2; } sr_[SDEPTH];
;     ...
;   f32x16 pA0, pA1, pB0, pB1; float alA, alB; bf16x8 pa0, pa1, pa2, pa3; const int NT = T / KVBLK;
;   constexpr int SE = 0, SO = SDEPTH - 1;
;   SLOAD(SE, 0); asm volatile("s_waitcnt vmcnt(0)" ::: "memory"); SWRITE(0, SE); __syncthreads();
;   qkt(pA0, pA1, K_lds, qr, qL, r32, hi, 0.f); partialSM<true>(pA0, pA1, m_reg, alA);
;   SLOAD(SO, KVBLK); if constexpr (SDEPTH == 2) { if (2 < NT) SLOAD(SE, 2 * KVBLK); }
;   SWAIT(); SWRITE(1, SO); __syncthreads();
	global_load_lds_dwordx4 v182, s[24:25]
	s_add_i32 m0, s43, 16384
	s_nop 0
	global_load_lds_dwordx4 v184, s[26:27]
	s_add_i32 m0, s43, 24576
	s_nop 0
	global_load_lds_dwordx4 v186, s[26:27]
	v_add_u32_e32 v178, v188, v178
	v_add_u32_e32 v180, v190, v180
	v_add_u32_e32 v182, v192, v182
	s_add_u32 s26, s26, 0x4000
	s_addc_u32 s27, s27, 0
	v_and_b32_e32 v247, 3, v243
	v_xor_b32_e32 v247, v247, v244
	v_mul_u32_u24_e32 v248, 0x180, v243
	v_lshl_add_u32 v248, v247, 4, v248
	v_add_u32_e32 v248, 49152, v248
	v_bfe_u32 v247, v243, 2, 1
	v_lshlrev_b32_e32 v247, 6, v247
	v_add_u32_e32 v202, v248, v247
	v_sub_u32_e32 v203, v248, v247
	v_add_u32_e32 v203, 64, v203
	v_add_u32_e32 v204, 24576, v202
	v_add_u32_e32 v205, 24576, v203
	v_add_u32_e32 v206, 49152, v202
	v_add_u32_e32 v207, 49152, v203
	v_bfe_u32 v247, v234, 4, 1
	v_bfe_u32 v248, v234, 2, 2
	v_lshl_or_b32 v247, v247, 2, v248
	v_lshrrev_b32_e32 v248, 5, v234
	v_lshlrev_b32_e32 v248, 11, v248
	v_and_b32_e32 v249, 3, v234
	v_lshl_or_b32 v248, v249, 3, v248
	v_xor_b32_e32 v249, 0, v247
	v_lshl_add_u32 v208, v249, 5, v248
	v_xor_b32_e32 v249, 1, v247
	v_lshl_add_u32 v209, v249, 5, v248
	v_add_u32_e32 v209, 256, v209
	v_xor_b32_e32 v249, 2, v247
	v_lshl_add_u32 v210, v249, 5, v248
	v_add_u32_e32 v210, 512, v210
	v_xor_b32_e32 v249, 3, v247
	v_lshl_add_u32 v211, v249, 5, v248
	v_add_u32_e32 v211, 768, v211
	v_xor_b32_e32 v249, 4, v247
	v_lshl_add_u32 v212, v249, 5, v248
	v_add_u32_e32 v212, 1024, v212
	v_xor_b32_e32 v249, 5, v247
	v_lshl_add_u32 v213, v249, 5, v248
	v_add_u32_e32 v213, 1280, v213
	v_xor_b32_e32 v249, 6, v247
	v_lshl_add_u32 v214, v249, 5, v248
	v_add_u32_e32 v214, 1536, v214
	v_xor_b32_e32 v249, 7, v247
	v_lshl_add_u32 v215, v249, 5, v248
	v_add_u32_e32 v215, 1792, v215
	s_lshl_b32 s41, s40, 8
	s_add_u32 s41, s41, 122880
	v_lshl_add_u32 v216, v243, 2, s41
	v_lshl_add_u32 v217, v244, 4, s41
	v_xor_b32_e32 v112, 16, v234
	v_lshlrev_b32_e32 v112, 2, v112
	v_mov_b32_e32 v218, 0
	v_mov_b32_e32 v220, 0
	v_mov_b32_e32 v224, 0
	v_mov_b32_e32 v225, 0
	v_mov_b32_e32 v226, 0
	v_mov_b32_e32 v227, 0
	v_mov_b32_e32 v219, 0
	v_mov_b32_e32 v221, 0
	v_mov_b32_e32 v228, 0
	v_mov_b32_e32 v229, 0
	v_mov_b32_e32 v230, 0
	v_mov_b32_e32 v231, 0
	v_mov_b32_e32 v0, 0
	v_mov_b32_e32 v1, 0
	v_mov_b32_e32 v2, 0
	v_mov_b32_e32 v3, 0
	v_mov_b32_e32 v4, 0
	v_mov_b32_e32 v5, 0
	v_mov_b32_e32 v6, 0
	v_mov_b32_e32 v7, 0
	v_mov_b32_e32 v8, 0
	v_mov_b32_e32 v9, 0
	v_mov_b32_e32 v10, 0
	v_mov_b32_e32 v11, 0
	v_mov_b32_e32 v12, 0
	v_mov_b32_e32 v13, 0
	v_mov_b32_e32 v14, 0
	v_mov_b32_e32 v15, 0
	v_mov_b32_e32 v16, 0
	v_mov_b32_e32 v17, 0
	v_mov_b32_e32 v18, 0
	v_mov_b32_e32 v19, 0
	v_mov_b32_e32 v20, 0
	v_mov_b32_e32 v21, 0
	v_mov_b32_e32 v22, 0
	v_mov_b32_e32 v23, 0
	v_mov_b32_e32 v24, 0
	v_mov_b32_e32 v25, 0
	v_mov_b32_e32 v26, 0
	v_mov_b32_e32 v27, 0
	v_mov_b32_e32 v28, 0
	v_mov_b32_e32 v29, 0
	v_mov_b32_e32 v30, 0
	v_mov_b32_e32 v31, 0
	v_mov_b32_e32 v32, 0
	v_mov_b32_e32 v33, 0
	v_mov_b32_e32 v34, 0
	v_mov_b32_e32 v35, 0
	v_mov_b32_e32 v36, 0
	v_mov_b32_e32 v37, 0
	v_mov_b32_e32 v38, 0
	v_mov_b32_e32 v39, 0
	v_mov_b32_e32 v40, 0
	v_mov_b32_e32 v41, 0
	v_mov_b32_e32 v42, 0
	v_mov_b32_e32 v43, 0
	v_mov_b32_e32 v44, 0
	v_mov_b32_e32 v45, 0
	v_mov_b32_e32 v46, 0
	v_mov_b32_e32 v47, 0
	v_mov_b32_e32 v48, 0
	v_mov_b32_e32 v49, 0
	v_mov_b32_e32 v50, 0
	v_mov_b32_e32 v51, 0
	v_mov_b32_e32 v52, 0
	v_mov_b32_e32 v53, 0
	v_mov_b32_e32 v54, 0
	v_mov_b32_e32 v55, 0
	v_mov_b32_e32 v56, 0
	v_mov_b32_e32 v57, 0
	v_mov_b32_e32 v58, 0
	v_mov_b32_e32 v59, 0
	v_mov_b32_e32 v60, 0
	v_mov_b32_e32 v61, 0
	v_mov_b32_e32 v62, 0
	v_mov_b32_e32 v63, 0
	s_waitcnt vmcnt(5)
	s_barrier
; template <bool FIRST>
; __device__ __forceinline__ void partialSM(f32x16& p0, f32x16& p1, float& m_reg, float& alpha) {
;   constexpr float THR2 = THR * 1.4426950408889634f;
;   float pmax = p0[0];
; #pragma unroll
;   for (int r = 1; r < 16; ++r) pmax = fmaxf(pmax, p0[r]);
; #pragma unroll
;   for (int r = 0; r < 16; ++r) pmax = fmaxf(pmax, p1[r]);
;   { auto rr = __builtin_amdgcn_permlane32_swap(__float_as_uint(pmax), __float_as_uint(pmax), false, false);
;     pmax = fmaxf(__uint_as_float(rr[0]), __uint_as_float(rr[1])); }
; __device__ __forceinline__ void qkt(f32x16& p0, f32x16& p1, const char* Ks, const bf16x8* qr, const char* qL, int r32, int hi, float negm) {
; #pragma unroll
;   for (int r = 0; r < 16; ++r) { p0[r] = negm; p1[r] = negm; }
; #pragma unroll
;   for (int d0 = 0; d0 < 12; ++d0) { int cb = (d0 * 16 + hi * 8) * 2;
;     bf16x8 b0 = *reinterpret_cast<const bf16x8*>(Ks + KSWZ(r32, cb));
;     bf16x8 b1 = *reinterpret_cast<const bf16x8*>(Ks + KSWZ(32 + r32, cb));
;     const bf16x8 q = d0 < 8 ? qr[d0 < 8 ? d0 : 0] : *reinterpret_cast<const bf16x8*>(qL + (d0 - 8) * 1024);
;     p0 = __builtin_amdgcn_mfma_f32_32x32x16_bf16(b0, q, p0, 0, 0, 0);
;     p1 = __builtin_amdgcn_mfma_f32_32x32x16_bf16(b1, q, p1, 0, 0, 0); }
; }
	s_add_i32 m0, s43, 98304
	s_nop 0
	global_load_lds_dwordx4 v178, s[24:25]
	s_add_i32 m0, s43, 106496
	s_nop 0
	global_load_lds_dwordx4 v180, s[24:25]
	s_add_i32 m0, s43, 114688
	s_nop 0
	global_load_lds_dwordx4 v182, s[24:25]
	s_add_i32 m0, s43, 32768
	s_nop 0
	global_load_lds_dwordx4 v184, s[26:27]
	s_add_i32 m0, s43, 40960
	s_nop 0
	global_load_lds_dwordx4 v186, s[26:27]
	v_add_u32_e32 v178, v188, v178
	v_add_u32_e32 v180, v190, v180
	v_add_u32_e32 v182, v192, v182
	s_add_u32 s26, s26, 0x4000
	s_addc_u32 s27, s27, 0
	ds_read_b128 v[162:165], v202 offset:0
	ds_read_b128 v[166:169], v202 offset:6144
	ds_read_b128 v[170:173], v202 offset:12288
	s_waitcnt lgkmcnt(2)
	v_mfma_f32_16x16x32_bf16 v[114:117], v[162:165], v[64:67], v[224:227]
	v_mfma_f32_16x16x32_bf16 v[118:121], v[162:165], v[88:91], v[228:231]
	ds_read_b128 v[174:177], v202 offset:18432
	s_waitcnt lgkmcnt(2)
	v_mfma_f32_16x16x32_bf16 v[126:129], v[166:169], v[88:91], v[228:231]
	v_mfma_f32_16x16x32_bf16 v[122:125], v[166:169], v[64:67], v[224:227]
	ds_read_b128 v[162:165], v203 offset:0
	s_waitcnt lgkmcnt(2)
	v_mfma_f32_16x16x32_bf16 v[130:133], v[170:173], v[64:67], v[224:227]
	v_mfma_f32_16x16x32_bf16 v[134:137], v[170:173], v[88:91], v[228:231]
	ds_read_b128 v[166:169], v203 offset:6144
	s_waitcnt lgkmcnt(2)
	v_mfma_f32_16x16x32_bf16 v[142:145], v[174:177], v[88:91], v[228:231]
	v_mfma_f32_16x16x32_bf16 v[138:141], v[174:177], v[64:67], v[224:227]
	ds_read_b128 v[170:173], v203 offset:12288
	s_waitcnt lgkmcnt(2)
	v_mfma_f32_16x16x32_bf16 v[114:117], v[162:165], v[68:71], v[114:117]
	v_mfma_f32_16x16x32_bf16 v[118:121], v[162:165], v[92:95], v[118:121]
	ds_read_b128 v[174:177], v203 offset:18432
	s_waitcnt lgkmcnt(2)
	v_mfma_f32_16x16x32_bf16 v[126:129], v[166:169], v[92:95], v[126:129]
	v_mfma_f32_16x16x32_bf16 v[122:125], v[166:169], v[68:71], v[122:125]
	ds_read_b128 v[162:165], v202 offset:128
	s_waitcnt lgkmcnt(2)
	v_mfma_f32_16x16x32_bf16 v[130:133], v[170:173], v[68:71], v[130:133]
	v_mfma_f32_16x16x32_bf16 v[134:137], v[170:173], v[92:95], v[134:137]
	ds_read_b128 v[166:169], v202 offset:6272
	s_waitcnt lgkmcnt(2)
	v_mfma_f32_16x16x32_bf16 v[142:145], v[174:177], v[92:95], v[142:145]
	v_mfma_f32_16x16x32_bf16 v[138:141], v[174:177], v[68:71], v[138:141]
	ds_read_b128 v[170:173], v202 offset:12416
	s_waitcnt lgkmcnt(2)
	v_mfma_f32_16x16x32_bf16 v[114:117], v[162:165], v[72:75], v[114:117]
	v_mfma_f32_16x16x32_bf16 v[118:121], v[162:165], v[96:99], v[118:121]
	ds_read_b128 v[174:177], v202 offset:18560
	s_waitcnt lgkmcnt(2)
	v_mfma_f32_16x16x32_bf16 v[126:129], v[166:169], v[96:99], v[126:129]
	v_mfma_f32_16x16x32_bf16 v[122:125], v[166:169], v[72:75], v[122:125]
	ds_read_b128 v[162:165], v203 offset:128
	s_waitcnt lgkmcnt(2)
	v_mfma_f32_16x16x32_bf16 v[130:133], v[170:173], v[72:75], v[130:133]
	v_mfma_f32_16x16x32_bf16 v[134:137], v[170:173], v[96:99], v[134:137]
	ds_read_b128 v[166:169], v203 offset:6272
	s_waitcnt lgkmcnt(2)
	v_mfma_f32_16x16x32_bf16 v[142:145], v[174:177], v[96:99], v[142:145]
	v_mfma_f32_16x16x32_bf16 v[138:141], v[174:177], v[72:75], v[138:141]
	ds_read_b128 v[170:173], v203 offset:12416
	s_waitcnt lgkmcnt(2)
	v_mfma_f32_16x16x32_bf16 v[114:117], v[162:165], v[76:79], v[114:117]
	v_mfma_f32_16x16x32_bf16 v[118:121], v[162:165], v[100:103], v[118:121]
	ds_read_b128 v[174:177], v203 offset:18560
	s_waitcnt lgkmcnt(2)
	v_mfma_f32_16x16x32_bf16 v[126:129], v[166:169], v[100:103], v[126:129]
	v_mfma_f32_16x16x32_bf16 v[122:125], v[166:169], v[76:79], v[122:125]
	ds_read_b128 v[162:165], v202 offset:256
	s_waitcnt lgkmcnt(2)
	v_mfma_f32_16x16x32_bf16 v[130:133], v[170:173], v[76:79], v[130:133]
	v_mfma_f32_16x16x32_bf16 v[134:137], v[170:173], v[100:103], v[134:137]
	ds_read_b128 v[166:169], v202 offset:6400
	s_waitcnt lgkmcnt(2)
	v_mfma_f32_16x16x32_bf16 v[142:145], v[174:177], v[100:103], v[142:145]
	v_mfma_f32_16x16x32_bf16 v[138:141], v[174:177], v[76:79], v[138:141]
	ds_read_b128 v[170:173], v202 offset:12544
	s_waitcnt lgkmcnt(2)
	v_mfma_f32_16x16x32_bf16 v[114:117], v[162:165], v[80:83], v[114:117]
	v_mfma_f32_16x16x32_bf16 v[118:121], v[162:165], v[104:107], v[118:121]
	ds_read_b128 v[174:177], v202 offset:18688
	s_waitcnt lgkmcnt(2)
	v_mfma_f32_16x16x32_bf16 v[126:129], v[166:169], v[104:107], v[126:129]
	v_mfma_f32_16x16x32_bf16 v[122:125], v[166:169], v[80:83], v[122:125]
	ds_read_b128 v[162:165], v203 offset:256
	s_waitcnt lgkmcnt(2)
	v_mfma_f32_16x16x32_bf16 v[130:133], v[170:173], v[80:83], v[130:133]
	v_mfma_f32_16x16x32_bf16 v[134:137], v[170:173], v[104:107], v[134:137]
	ds_read_b128 v[166:169], v203 offset:6400
	s_waitcnt lgkmcnt(2)
	v_mfma_f32_16x16x32_bf16 v[142:145], v[174:177], v[104:107], v[142:145]
	v_mfma_f32_16x16x32_bf16 v[138:141], v[174:177], v[80:83], v[138:141]
	ds_read_b128 v[170:173], v203 offset:12544
	s_waitcnt lgkmcnt(2)
	v_mfma_f32_16x16x32_bf16 v[114:117], v[162:165], v[84:87], v[114:117]
	v_mfma_f32_16x16x32_bf16 v[118:121], v[162:165], v[108:111], v[118:121]
	ds_read_b128 v[174:177], v203 offset:18688
	s_waitcnt lgkmcnt(2)
	v_mfma_f32_16x16x32_bf16 v[126:129], v[166:169], v[108:111], v[126:129]
	v_mfma_f32_16x16x32_bf16 v[122:125], v[166:169], v[84:87], v[122:125]
	s_waitcnt lgkmcnt(1)
	v_mfma_f32_16x16x32_bf16 v[130:133], v[170:173], v[84:87], v[130:133]
	v_mfma_f32_16x16x32_bf16 v[134:137], v[170:173], v[108:111], v[134:137]
	s_waitcnt lgkmcnt(0)
	v_mfma_f32_16x16x32_bf16 v[142:145], v[174:177], v[108:111], v[142:145]
	v_mfma_f32_16x16x32_bf16 v[138:141], v[174:177], v[84:87], v[138:141]
	ds_read_b64_tr_b16 v[162:163], v208 offset:0
	ds_read_b64_tr_b16 v[164:165], v208 offset:4096
	ds_read_b64_tr_b16 v[166:167], v209 offset:0
	ds_read_b64_tr_b16 v[168:169], v209 offset:4096
	ds_read_b64_tr_b16 v[170:171], v210 offset:0
	ds_read_b64_tr_b16 v[172:173], v210 offset:4096
	s_nop 7
	v_max3_f32 v232, v114, v115, v116
	v_max_f32_e32 v232, v232, v117
	v_max3_f32 v233, v118, v119, v120
	v_max_f32_e32 v233, v233, v121
	v_max3_f32 v232, v232, v122, v123
	v_max3_f32 v232, v232, v124, v125
	v_max3_f32 v233, v233, v126, v127
	v_max3_f32 v233, v233, v128, v129
	v_max3_f32 v232, v232, v130, v131
	v_max3_f32 v232, v232, v132, v133
	v_max3_f32 v233, v233, v134, v135
	v_max3_f32 v233, v233, v136, v137
	v_max3_f32 v232, v232, v138, v139
	v_max3_f32 v232, v232, v140, v141
	v_max3_f32 v233, v233, v142, v143
	v_max3_f32 v233, v233, v144, v145
	s_branch .Lat_rare_0

; #define SBAR() __builtin_amdgcn_sched_barrier(0)
; #define SLOAD(i, k0) do { sr_[i].vs0 = *(const bf16x8*)(&Vh[(long)((k0) + sr) * 128 + sc]); sr_[i].vs1 = *(const bf16x8*)(&Vh[(long)((k0) + 32 + sr) * 128 + sc]); \
;     sr_[i].ks0 = *(const bf16x8*)(&Kn[(long)((k0) + sr) * 128 + sc]); sr_[i].ks1 = *(const bf16x8*)(&Kn[(long)((k0) + 32 + sr) * 128 + sc]); \
;     sr_[i].ks2 = *(const bf16x8*)(&Kr[(long)((k0) + rr) * 64 + rc]); } while (0)
; template <bool FIRST>
; __device__ __forceinline__ void partialSM(f32x16& p0, f32x16& p1, float& m_reg, float& alpha) {
;   constexpr float THR2 = THR * 1.4426950408889634f;
;   float pmax = p0[0];
; #pragma unroll
;   for (int r = 1; r < 16; ++r) pmax = fmaxf(pmax, p0[r]);
; #pragma unroll
;   for (int r = 0; r < 16; ++r) pmax = fmaxf(pmax, p1[r]);
;   { auto rr = __builtin_amdgcn_permlane32_swap(__float_as_uint(pmax), __float_as_uint(pmax), false, false);
;     pmax = fmaxf(__uint_as_float(rr[0]), __uint_as_float(rr[1])); }
;   if (!FIRST && __builtin_expect(__all(pmax <= THR2), 1)) { alpha = 1.f; }
; __device__ __forceinline__ void attn_unit(const bf16_t* __restrict__ Qb, const bf16_t* __restrict__ Kn, const bf16_t* __restrict__ Kr, const bf16_t* __restrict__ Vh,
;                                           bf16_t* __restrict__ Ob, char* lds) {
;     ...
;   for (int j = 1; j + 1 < NT; j += 2) {
;     SBAR(); qkt(pB0, pB1, K_lds + SHM_K, qr, qL, r32, hi, -m_reg);
;     finishSM(pA0, pA1, alA, l_reg, pa0, pa1, pa2, pa3); SBAR();
;     SLOAD(SO, (j + SDEPTH) * KVBLK); SBAR();
;     pv_d0(o, vb0, pa0, pa1, pa2, pa3); partialSM<false>(pB0, pB1, m_reg, alB);
.Lat_loop:
	s_add_i32 m0, s43, 49152
	s_nop 0
	global_load_lds_dwordx4 v178, s[24:25]
	s_add_i32 m0, s43, 57344
	s_nop 0
	global_load_lds_dwordx4 v180, s[24:25]
	s_add_i32 m0, s43, 65536
	s_nop 0
	global_load_lds_dwordx4 v182, s[24:25]
	s_add_i32 m0, s43, 0
	s_nop 0
	global_load_lds_dwordx4 v184, s[26:27]
	s_add_i32 m0, s43, 8192
	s_nop 0
	global_load_lds_dwordx4 v186, s[26:27]
	v_add_u32_e32 v178, v188, v178
	v_add_u32_e32 v180, v190, v180
	v_add_u32_e32 v182, v192, v182
	s_add_u32 s26, s26, 0x4000
	s_addc_u32 s27, s27, 0
	ds_read_b128 v[162:165], v204 offset:0
	ds_read_b128 v[166:169], v204 offset:6144
	ds_read_b128 v[170:173], v204 offset:12288
	s_waitcnt lgkmcnt(2)
	v_mfma_f32_16x16x32_bf16 v[114:117], v[162:165], v[64:67], v[224:227]
	v_mfma_f32_16x16x32_bf16 v[118:121], v[162:165], v[88:91], v[228:231]
	ds_read_b128 v[174:177], v204 offset:18432
	s_waitcnt lgkmcnt(2)
	v_mfma_f32_16x16x32_bf16 v[126:129], v[166:169], v[88:91], v[228:231]
	v_mfma_f32_16x16x32_bf16 v[122:125], v[166:169], v[64:67], v[224:227]
	ds_read_b128 v[162:165], v205 offset:0
	s_waitcnt lgkmcnt(2)
	v_mfma_f32_16x16x32_bf16 v[130:133], v[170:173], v[64:67], v[224:227]
	v_mfma_f32_16x16x32_bf16 v[134:137], v[170:173], v[88:91], v[228:231]
	ds_read_b128 v[166:169], v205 offset:6144
	s_waitcnt lgkmcnt(2)
	v_mfma_f32_16x16x32_bf16 v[142:145], v[174:177], v[88:91], v[228:231]
	v_mfma_f32_16x16x32_bf16 v[138:141], v[174:177], v[64:67], v[224:227]
	ds_read_b128 v[170:173], v205 offset:12288
	s_waitcnt lgkmcnt(2)
	v_mfma_f32_16x16x32_bf16 v[114:117], v[162:165], v[68:71], v[114:117]
	v_mfma_f32_16x16x32_bf16 v[118:121], v[162:165], v[92:95], v[118:121]
	ds_read_b128 v[174:177], v205 offset:18432
	s_waitcnt lgkmcnt(2)
	v_mfma_f32_16x16x32_bf16 v[126:129], v[166:169], v[92:95], v[126:129]
	v_mfma_f32_16x16x32_bf16 v[122:125], v[166:169], v[68:71], v[122:125]
	ds_read_b128 v[162:165], v204 offset:128
	s_waitcnt lgkmcnt(2)
	v_mfma_f32_16x16x32_bf16 v[130:133], v[170:173], v[68:71], v[130:133]
	v_mfma_f32_16x16x32_bf16 v[134:137], v[170:173], v[92:95], v[134:137]
	ds_read_b128 v[166:169], v204 offset:6272
	s_waitcnt lgkmcnt(2)
	v_mfma_f32_16x16x32_bf16 v[142:145], v[174:177], v[92:95], v[142:145]
	v_mfma_f32_16x16x32_bf16 v[138:141], v[174:177], v[68:71], v[138:141]
	ds_read_b128 v[170:173], v204 offset:12416
	s_waitcnt lgkmcnt(2)
	v_mfma_f32_16x16x32_bf16 v[114:117], v[162:165], v[72:75], v[114:117]
	v_mfma_f32_16x16x32_bf16 v[118:121], v[162:165], v[96:99], v[118:121]
	ds_read_b128 v[174:177], v204 offset:18560
	s_waitcnt lgkmcnt(2)
	v_mfma_f32_16x16x32_bf16 v[126:129], v[166:169], v[96:99], v[126:129]
	v_mfma_f32_16x16x32_bf16 v[122:125], v[166:169], v[72:75], v[122:125]
	ds_read_b128 v[162:165], v205 offset:128
	s_waitcnt lgkmcnt(2)
	v_mfma_f32_16x16x32_bf16 v[130:133], v[170:173], v[72:75], v[130:133]
	v_mfma_f32_16x16x32_bf16 v[134:137], v[170:173], v[96:99], v[134:137]
	ds_read_b128 v[166:169], v205 offset:6272
	s_waitcnt lgkmcnt(2)
	v_mfma_f32_16x16x32_bf16 v[142:145], v[174:177], v[96:99], v[142:145]
	v_mfma_f32_16x16x32_bf16 v[138:141], v[174:177], v[72:75], v[138:141]
	ds_read_b128 v[170:173], v205 offset:12416
	s_waitcnt lgkmcnt(2)
	v_mfma_f32_16x16x32_bf16 v[114:117], v[162:165], v[76:79], v[114:117]
	v_mfma_f32_16x16x32_bf16 v[118:121], v[162:165], v[100:103], v[118:121]
	ds_read_b128 v[174:177], v205 offset:18560
	s_waitcnt lgkmcnt(2)
	v_mfma_f32_16x16x32_bf16 v[126:129], v[166:169], v[100:103], v[126:129]
	v_mfma_f32_16x16x32_bf16 v[122:125], v[166:169], v[76:79], v[122:125]
	ds_read_b128 v[162:165], v204 offset:256
	s_waitcnt lgkmcnt(2)
	v_mfma_f32_16x16x32_bf16 v[130:133], v[170:173], v[76:79], v[130:133]
	v_mfma_f32_16x16x32_bf16 v[134:137], v[170:173], v[100:103], v[134:137]
	ds_read_b128 v[166:169], v204 offset:6400
	s_waitcnt lgkmcnt(2)
	v_mfma_f32_16x16x32_bf16 v[142:145], v[174:177], v[100:103], v[142:145]
	v_mfma_f32_16x16x32_bf16 v[138:141], v[174:177], v[76:79], v[138:141]
	ds_read_b128 v[170:173], v204 offset:12544
	s_waitcnt lgkmcnt(2)
	v_mfma_f32_16x16x32_bf16 v[114:117], v[162:165], v[80:83], v[114:117]
	v_mfma_f32_16x16x32_bf16 v[118:121], v[162:165], v[104:107], v[118:121]
	ds_read_b128 v[174:177], v204 offset:18688
	s_waitcnt lgkmcnt(2)
	v_mfma_f32_16x16x32_bf16 v[126:129], v[166:169], v[104:107], v[126:129]
	v_mfma_f32_16x16x32_bf16 v[122:125], v[166:169], v[80:83], v[122:125]
	ds_read_b128 v[162:165], v205 offset:256
	s_waitcnt lgkmcnt(2)
	v_mfma_f32_16x16x32_bf16 v[130:133], v[170:173], v[80:83], v[130:133]
	v_mfma_f32_16x16x32_bf16 v[134:137], v[170:173], v[104:107], v[134:137]
	ds_read_b128 v[166:169], v205 offset:6400
	s_waitcnt lgkmcnt(2)
	v_mfma_f32_16x16x32_bf16 v[142:145], v[174:177], v[104:107], v[142:145]
	v_mfma_f32_16x16x32_bf16 v[138:141], v[174:177], v[80:83], v[138:141]
	ds_read_b128 v[170:173], v205 offset:12544
	s_waitcnt lgkmcnt(2)
	v_mfma_f32_16x16x32_bf16 v[114:117], v[162:165], v[84:87], v[114:117]
	v_mfma_f32_16x16x32_bf16 v[118:121], v[162:165], v[108:111], v[118:121]
	ds_read_b128 v[174:177], v205 offset:18688
	s_waitcnt lgkmcnt(2)
	v_mfma_f32_16x16x32_bf16 v[126:129], v[166:169], v[108:111], v[126:129]
	v_mfma_f32_16x16x32_bf16 v[122:125], v[166:169], v[84:87], v[122:125]
	s_waitcnt lgkmcnt(1)
	v_mfma_f32_16x16x32_bf16 v[130:133], v[170:173], v[84:87], v[130:133]
	v_mfma_f32_16x16x32_bf16 v[134:137], v[170:173], v[108:111], v[134:137]
	s_waitcnt lgkmcnt(0)
	v_mfma_f32_16x16x32_bf16 v[142:145], v[174:177], v[108:111], v[142:145]
	v_mfma_f32_16x16x32_bf16 v[138:141], v[174:177], v[84:87], v[138:141]
	ds_read_b64_tr_b16 v[162:163], v208 offset:16384
	ds_read_b64_tr_b16 v[164:165], v208 offset:20480
	ds_read_b64_tr_b16 v[166:167], v209 offset:16384
	ds_read_b64_tr_b16 v[168:169], v209 offset:20480
	ds_read_b64_tr_b16 v[170:171], v210 offset:16384
	ds_read_b64_tr_b16 v[172:173], v210 offset:20480
	s_nop 7
	v_max3_f32 v232, v114, v115, v116
	v_max_f32_e32 v232, v232, v117
	v_max3_f32 v233, v118, v119, v120
	v_max_f32_e32 v233, v233, v121
	v_max3_f32 v232, v232, v122, v123
	v_max3_f32 v232, v232, v124, v125
	v_max3_f32 v233, v233, v126, v127
	v_max3_f32 v233, v233, v128, v129
	v_max3_f32 v232, v232, v130, v131
	v_max3_f32 v232, v232, v132, v133
	v_max3_f32 v233, v233, v134, v135
	v_max3_f32 v233, v233, v136, v137
	v_max3_f32 v232, v232, v138, v139
	v_max3_f32 v232, v232, v140, v141
	v_max3_f32 v233, v233, v142, v143
	v_max3_f32 v233, v233, v144, v145
	v_max_f32_e32 v234, v232, v233
	v_cmp_ge_f32_e32 vcc, s38, v234
	s_cmp_eq_u64 vcc, exec
	s_cbranch_scc0 .Lat_rare_1
; #define SBAR() __builtin_amdgcn_sched_barrier(0)
; __device__ __forceinline__ void finishSM(f32x16& p0, f32x16& p1, float alpha, float& l_reg, bf16x8& pa0, bf16x8& pa1, bf16x8& pa2, bf16x8& pa3) {
; #pragma unroll
;   for (int r = 0; r < 16; ++r) p1[r] = __builtin_amdgcn_exp2f(p1[r]);
;   float ps = 0;
; #pragma unroll
;   for (int r = 0; r < 16; ++r) ps += p0[r];
; #pragma unroll
;   for (int r = 0; r < 16; ++r) ps += p1[r];
;   { auto rr = __builtin_amdgcn_permlane32_swap(__float_as_uint(ps), __float_as_uint(ps), false, false);
;     ps = __uint_as_float(rr[0]) + __uint_as_float(rr[1]); }
;   l_reg = l_reg * alpha + ps;
;     ...
;   PK4(p0, 0, pa0); PK4(p0, 8, pa1); PK4(p1, 0, pa2); PK4(p1, 8, pa3);
;     ...
; }
; template <int D0> __device__ __forceinline__ void pv_one(f32x16& od, int vb, bf16x8 pa0, bf16x8 pa1, bf16x8 pa2, bf16x8 pa3) {
;   const s16x4 l0 = tr_read<v_rd_off(D0, 0, 0)>(vb), h0 = tr_read<v_rd_off(D0, 0, 1)>(vb), l1 = tr_read<v_rd_off(D0, 1, 0)>(vb), h1 = tr_read<v_rd_off(D0, 1, 1)>(vb);
;   const s16x4 l2 = tr_read<v_rd_off(D0, 2, 0)>(vb), h2 = tr_read<v_rd_off(D0, 2, 1)>(vb), l3 = tr_read<v_rd_off(D0, 3, 0)>(vb), h3 = tr_read<v_rd_off(D0, 3, 1)>(vb);
;   asm volatile("s_waitcnt lgkmcnt(0)" ::: "memory"); SBAR();
;     ...
;   od = __builtin_amdgcn_mfma_f32_32x32x16_bf16(pa0, PK(l0, h0), od, 0, 0, 0);
;   od = __builtin_amdgcn_mfma_f32_32x32x16_bf16(pa1, PK(l1, h1), od, 0, 0, 0);
;   od = __builtin_amdgcn_mfma_f32_32x32x16_bf16(pa2, PK(l2, h2), od, 0, 0, 0);
;   od = __builtin_amdgcn_mfma_f32_32x32x16_bf16(pa3, PK(l3, h3), od, 0, 0, 0);
;     ...
; }
; __device__ __forceinline__ void pv_d0(f32x16* o, int vb, bf16x8 pa0, bf16x8 pa1, bf16x8 pa2, bf16x8 pa3) {
;   pv_one<0>(o[0], vb, pa0, pa1, pa2, pa3); pv_one<1>(o[1], vb, pa0, pa1, pa2, pa3); pv_one<2>(o[2], vb, pa0, pa1, pa2, pa3); pv_one<3>(o[3], vb, pa0, pa1, pa2, pa3);
.Lat_cont_1:
	v_exp_f32_e32 v114, v114
	v_exp_f32_e32 v115, v115
	v_exp_f32_e32 v116, v116
	v_exp_f32_e32 v117, v117
	v_add_f32_e32 v220, v220, v114
	v_add_f32_e32 v220, v220, v115
	v_add_f32_e32 v220, v220, v116
	v_add_f32_e32 v220, v220, v117
	v_exp_f32_e32 v122, v122
	v_exp_f32_e32 v123, v123
	v_exp_f32_e32 v124, v124
	v_exp_f32_e32 v125, v125
	v_add_f32_e32 v220, v220, v122
	v_add_f32_e32 v220, v220, v123
	v_add_f32_e32 v220, v220, v124
	v_add_f32_e32 v220, v220, v125
	v_cvt_pk_bf16_f32 v146, v114, v115
	v_cvt_pk_bf16_f32 v147, v116, v117
	v_cvt_pk_bf16_f32 v148, v122, v123
	v_cvt_pk_bf16_f32 v149, v124, v125
	v_exp_f32_e32 v118, v118
	v_exp_f32_e32 v119, v119
	v_exp_f32_e32 v120, v120
	v_exp_f32_e32 v121, v121
	v_add_f32_e32 v221, v221, v118
	v_add_f32_e32 v221, v221, v119
	v_add_f32_e32 v221, v221, v120
	v_add_f32_e32 v221, v221, v121
	v_exp_f32_e32 v126, v126
	v_exp_f32_e32 v127, v127
	v_exp_f32_e32 v128, v128
	v_exp_f32_e32 v129, v129
	v_add_f32_e32 v221, v221, v126
	v_add_f32_e32 v221, v221, v127
	v_add_f32_e32 v221, v221, v128
	v_add_f32_e32 v221, v221, v129
	v_cvt_pk_bf16_f32 v154, v118, v119
	v_cvt_pk_bf16_f32 v155, v120, v121
	v_cvt_pk_bf16_f32 v156, v126, v127
	v_cvt_pk_bf16_f32 v157, v128, v129
	s_nop 1
	s_waitcnt lgkmcnt(4)
	v_mfma_f32_16x16x32_bf16 v[0:3], v[146:149], v[162:165], v[0:3]
	v_mfma_f32_16x16x32_bf16 v[32:35], v[154:157], v[162:165], v[32:35]
	ds_read_b64_tr_b16 v[174:175], v211 offset:16384
	ds_read_b64_tr_b16 v[176:177], v211 offset:20480
	v_exp_f32_e32 v130, v130
	v_exp_f32_e32 v131, v131
	v_exp_f32_e32 v132, v132
	v_exp_f32_e32 v133, v133
	v_add_f32_e32 v220, v220, v130
	s_waitcnt lgkmcnt(4)
	v_mfma_f32_16x16x32_bf16 v[36:39], v[154:157], v[166:169], v[36:39]
	v_mfma_f32_16x16x32_bf16 v[4:7], v[146:149], v[166:169], v[4:7]
	ds_read_b64_tr_b16 v[162:163], v212 offset:16384
	ds_read_b64_tr_b16 v[164:165], v212 offset:20480
	v_add_f32_e32 v220, v220, v131
	v_add_f32_e32 v220, v220, v132
	v_add_f32_e32 v220, v220, v133
	v_exp_f32_e32 v138, v138
	v_exp_f32_e32 v139, v139
	s_waitcnt lgkmcnt(4)
	v_mfma_f32_16x16x32_bf16 v[8:11], v[146:149], v[170:173], v[8:11]
	v_mfma_f32_16x16x32_bf16 v[40:43], v[154:157], v[170:173], v[40:43]
	ds_read_b64_tr_b16 v[166:167], v213 offset:16384
	ds_read_b64_tr_b16 v[168:169], v213 offset:20480
	v_exp_f32_e32 v140, v140
	v_exp_f32_e32 v141, v141
	v_add_f32_e32 v220, v220, v138
	v_add_f32_e32 v220, v220, v139
	v_add_f32_e32 v220, v220, v140
	s_waitcnt lgkmcnt(4)
	v_mfma_f32_16x16x32_bf16 v[44:47], v[154:157], v[174:177], v[44:47]
	v_mfma_f32_16x16x32_bf16 v[12:15], v[146:149], v[174:177], v[12:15]
	ds_read_b64_tr_b16 v[170:171], v214 offset:16384
	ds_read_b64_tr_b16 v[172:173], v214 offset:20480
	v_add_f32_e32 v220, v220, v141
	v_cvt_pk_bf16_f32 v150, v130, v131
	v_cvt_pk_bf16_f32 v151, v132, v133
	v_cvt_pk_bf16_f32 v152, v138, v139
	v_cvt_pk_bf16_f32 v153, v140, v141
	s_waitcnt lgkmcnt(4)
	v_mfma_f32_16x16x32_bf16 v[16:19], v[146:149], v[162:165], v[16:19]
	v_mfma_f32_16x16x32_bf16 v[48:51], v[154:157], v[162:165], v[48:51]
	ds_read_b64_tr_b16 v[174:175], v215 offset:16384
	ds_read_b64_tr_b16 v[176:177], v215 offset:20480
	v_exp_f32_e32 v134, v134
	v_exp_f32_e32 v135, v135
	v_exp_f32_e32 v136, v136
	v_exp_f32_e32 v137, v137
	v_add_f32_e32 v221, v221, v134
	s_waitcnt lgkmcnt(4)
	v_mfma_f32_16x16x32_bf16 v[52:55], v[154:157], v[166:169], v[52:55]
	v_mfma_f32_16x16x32_bf16 v[20:23], v[146:149], v[166:169], v[20:23]
	ds_read_b64_tr_b16 v[162:163], v208 offset:24576
	ds_read_b64_tr_b16 v[164:165], v208 offset:28672
	v_add_f32_e32 v221, v221, v135
	v_add_f32_e32 v221, v221, v136
	v_add_f32_e32 v221, v221, v137
	v_exp_f32_e32 v142, v142
	v_exp_f32_e32 v143, v143
	s_waitcnt lgkmcnt(4)
	v_mfma_f32_16x16x32_bf16 v[24:27], v[146:149], v[170:173], v[24:27]
	v_mfma_f32_16x16x32_bf16 v[56:59], v[154:157], v[170:173], v[56:59]
	ds_read_b64_tr_b16 v[166:167], v209 offset:24576
	ds_read_b64_tr_b16 v[168:169], v209 offset:28672
	v_exp_f32_e32 v144, v144
	v_exp_f32_e32 v145, v145
	v_add_f32_e32 v221, v221, v142
	v_add_f32_e32 v221, v221, v143
	v_add_f32_e32 v221, v221, v144
	s_waitcnt lgkmcnt(4)
	v_mfma_f32_16x16x32_bf16 v[60:63], v[154:157], v[174:177], v[60:63]
	v_mfma_f32_16x16x32_bf16 v[28:31], v[146:149], v[174:177], v[28:31]
	ds_read_b64_tr_b16 v[170:171], v210 offset:24576
	ds_read_b64_tr_b16 v[172:173], v210 offset:28672
	v_add_f32_e32 v221, v221, v145
	v_cvt_pk_bf16_f32 v158, v134, v135
	v_cvt_pk_bf16_f32 v159, v136, v137
	v_cvt_pk_bf16_f32 v160, v142, v143
	v_cvt_pk_bf16_f32 v161, v144, v145
	s_waitcnt lgkmcnt(4)
	s_nop 1
	v_mfma_f32_16x16x32_bf16 v[0:3], v[150:153], v[162:165], v[0:3]
	v_mfma_f32_16x16x32_bf16 v[32:35], v[158:161], v[162:165], v[32:35]
	ds_read_b64_tr_b16 v[174:175], v211 offset:24576
	ds_read_b64_tr_b16 v[176:177], v211 offset:28672
	s_waitcnt lgkmcnt(4)
	v_mfma_f32_16x16x32_bf16 v[36:39], v[158:161], v[166:169], v[36:39]
	v_mfma_f32_16x16x32_bf16 v[4:7], v[150:153], v[166:169], v[4:7]
	ds_read_b64_tr_b16 v[162:163], v212 offset:24576
	ds_read_b64_tr_b16 v[164:165], v212 offset:28672
	s_waitcnt lgkmcnt(4)
	v_mfma_f32_16x16x32_bf16 v[8:11], v[150:153], v[170:173], v[8:11]
	v_mfma_f32_16x16x32_bf16 v[40:43], v[158:161], v[170:173], v[40:43]
	ds_read_b64_tr_b16 v[166:167], v213 offset:24576
	ds_read_b64_tr_b16 v[168:169], v213 offset:28672
	s_waitcnt lgkmcnt(4)
	v_mfma_f32_16x16x32_bf16 v[44:47], v[158:161], v[174:177], v[44:47]
	v_mfma_f32_16x16x32_bf16 v[12:15], v[150:153], v[174:177], v[12:15]
	ds_read_b64_tr_b16 v[170:171], v214 offset:24576
	ds_read_b64_tr_b16 v[172:173], v214 offset:28672
	s_waitcnt lgkmcnt(4)
	v_mfma_f32_16x16x32_bf16 v[16:19], v[150:153], v[162:165], v[16:19]
	v_mfma_f32_16x16x32_bf16 v[48:51], v[158:161], v[162:165], v[48:51]
	ds_read_b64_tr_b16 v[174:175], v215 offset:24576
	ds_read_b64_tr_b16 v[176:177], v215 offset:28672
	s_waitcnt lgkmcnt(4)
	v_mfma_f32_16x16x32_bf16 v[52:55], v[158:161], v[166:169], v[52:55]
	v_mfma_f32_16x16x32_bf16 v[20:23], v[150:153], v[166:169], v[20:23]
	s_waitcnt lgkmcnt(2)
	v_mfma_f32_16x16x32_bf16 v[24:27], v[150:153], v[170:173], v[24:27]
	v_mfma_f32_16x16x32_bf16 v[56:59], v[158:161], v[170:173], v[56:59]
	s_waitcnt lgkmcnt(0)
	v_mfma_f32_16x16x32_bf16 v[60:63], v[158:161], v[174:177], v[60:63]
	v_mfma_f32_16x16x32_bf16 v[28:31], v[150:153], v[174:177], v[28:31]
	s_waitcnt vmcnt(5)
	s_barrier
; template <bool FIRST>
; __device__ __forceinline__ void partialSM(f32x16& p0, f32x16& p1, float& m_reg, float& alpha) {
;   constexpr float THR2 = THR * 1.4426950408889634f;
;   float pmax = p0[0];
; #pragma unroll
;   for (int r = 1; r < 16; ++r) pmax = fmaxf(pmax, p0[r]);
; #pragma unroll
;   for (int r = 0; r < 16; ++r) pmax = fmaxf(pmax, p1[r]);
;   { auto rr = __builtin_amdgcn_permlane32_swap(__float_as_uint(pmax), __float_as_uint(pmax), false, false);
;     pmax = fmaxf(__uint_as_float(rr[0]), __uint_as_float(rr[1])); }
;   if (!FIRST && __builtin_expect(__all(pmax <= THR2), 1)) { alpha = 1.f; }
; __device__ __forceinline__ void qkt(f32x16& p0, f32x16& p1, const char* Ks, const bf16x8* qr, const char* qL, int r32, int hi, float negm) {
; #pragma unroll
;   for (int r = 0; r < 16; ++r) { p0[r] = negm; p1[r] = negm; }
; #pragma unroll
;   for (int d0 = 0; d0 < 12; ++d0) { int cb = (d0 * 16 + hi * 8) * 2;
;     bf16x8 b0 = *reinterpret_cast<const bf16x8*>(Ks + KSWZ(r32, cb));
;     bf16x8 b1 = *reinterpret_cast<const bf16x8*>(Ks + KSWZ(32 + r32, cb));
;     const bf16x8 q = d0 < 8 ? qr[d0 < 8 ? d0 : 0] : *reinterpret_cast<const bf16x8*>(qL + (d0 - 8) * 1024);
;     p0 = __builtin_amdgcn_mfma_f32_32x32x16_bf16(b0, q, p0, 0, 0, 0);
;     p1 = __builtin_amdgcn_mfma_f32_32x32x16_bf16(b1, q, p1, 0, 0, 0); }
; }
	s_add_i32 m0, s43, 73728
	s_nop 0
	global_load_lds_dwordx4 v178, s[24:25]
	s_add_i32 m0, s43, 81920
	s_nop 0
	global_load_lds_dwordx4 v180, s[24:25]
	s_add_i32 m0, s43, 90112
	s_nop 0
	global_load_lds_dwordx4 v182, s[24:25]
	s_add_i32 m0, s43, 16384
	s_nop 0
	global_load_lds_dwordx4 v184, s[26:27]
	s_add_i32 m0, s43, 24576
	s_nop 0
	global_load_lds_dwordx4 v186, s[26:27]
	v_add_u32_e32 v178, v188, v178
	v_add_u32_e32 v180, v190, v180
	v_add_u32_e32 v182, v192, v182
	s_add_u32 s26, s26, 0x4000
	s_addc_u32 s27, s27, 0
	ds_read_b128 v[162:165], v206 offset:0
	ds_read_b128 v[166:169], v206 offset:6144
	ds_read_b128 v[170:173], v206 offset:12288
	s_waitcnt lgkmcnt(2)
	v_mfma_f32_16x16x32_bf16 v[114:117], v[162:165], v[64:67], v[224:227]
	v_mfma_f32_16x16x32_bf16 v[118:121], v[162:165], v[88:91], v[228:231]
	ds_read_b128 v[174:177], v206 offset:18432
	s_waitcnt lgkmcnt(2)
	v_mfma_f32_16x16x32_bf16 v[126:129], v[166:169], v[88:91], v[228:231]
	v_mfma_f32_16x16x32_bf16 v[122:125], v[166:169], v[64:67], v[224:227]
	ds_read_b128 v[162:165], v207 offset:0
	s_waitcnt lgkmcnt(2)
	v_mfma_f32_16x16x32_bf16 v[130:133], v[170:173], v[64:67], v[224:227]
	v_mfma_f32_16x16x32_bf16 v[134:137], v[170:173], v[88:91], v[228:231]
	ds_read_b128 v[166:169], v207 offset:6144
	s_waitcnt lgkmcnt(2)
	v_mfma_f32_16x16x32_bf16 v[142:145], v[174:177], v[88:91], v[228:231]
	v_mfma_f32_16x16x32_bf16 v[138:141], v[174:177], v[64:67], v[224:227]
	ds_read_b128 v[170:173], v207 offset:12288
	s_waitcnt lgkmcnt(2)
	v_mfma_f32_16x16x32_bf16 v[114:117], v[162:165], v[68:71], v[114:117]
	v_mfma_f32_16x16x32_bf16 v[118:121], v[162:165], v[92:95], v[118:121]
	ds_read_b128 v[174:177], v207 offset:18432
	s_waitcnt lgkmcnt(2)
	v_mfma_f32_16x16x32_bf16 v[126:129], v[166:169], v[92:95], v[126:129]
	v_mfma_f32_16x16x32_bf16 v[122:125], v[166:169], v[68:71], v[122:125]
	ds_read_b128 v[162:165], v206 offset:128
	s_waitcnt lgkmcnt(2)
	v_mfma_f32_16x16x32_bf16 v[130:133], v[170:173], v[68:71], v[130:133]
	v_mfma_f32_16x16x32_bf16 v[134:137], v[170:173], v[92:95], v[134:137]
	ds_read_b128 v[166:169], v206 offset:6272
	s_waitcnt lgkmcnt(2)
	v_mfma_f32_16x16x32_bf16 v[142:145], v[174:177], v[92:95], v[142:145]
	v_mfma_f32_16x16x32_bf16 v[138:141], v[174:177], v[68:71], v[138:141]
	ds_read_b128 v[170:173], v206 offset:12416
	s_waitcnt lgkmcnt(2)
	v_mfma_f32_16x16x32_bf16 v[114:117], v[162:165], v[72:75], v[114:117]
	v_mfma_f32_16x16x32_bf16 v[118:121], v[162:165], v[96:99], v[118:121]
	ds_read_b128 v[174:177], v206 offset:18560
	s_waitcnt lgkmcnt(2)
	v_mfma_f32_16x16x32_bf16 v[126:129], v[166:169], v[96:99], v[126:129]
	v_mfma_f32_16x16x32_bf16 v[122:125], v[166:169], v[72:75], v[122:125]
	ds_read_b128 v[162:165], v207 offset:128
	s_waitcnt lgkmcnt(2)
	v_mfma_f32_16x16x32_bf16 v[130:133], v[170:173], v[72:75], v[130:133]
	v_mfma_f32_16x16x32_bf16 v[134:137], v[170:173], v[96:99], v[134:137]
	ds_read_b128 v[166:169], v207 offset:6272
	s_waitcnt lgkmcnt(2)
	v_mfma_f32_16x16x32_bf16 v[142:145], v[174:177], v[96:99], v[142:145]
	v_mfma_f32_16x16x32_bf16 v[138:141], v[174:177], v[72:75], v[138:141]
	ds_read_b128 v[170:173], v207 offset:12416
	s_waitcnt lgkmcnt(2)
	v_mfma_f32_16x16x32_bf16 v[114:117], v[162:165], v[76:79], v[114:117]
	v_mfma_f32_16x16x32_bf16 v[118:121], v[162:165], v[100:103], v[118:121]
	ds_read_b128 v[174:177], v207 offset:18560
	s_waitcnt lgkmcnt(2)
	v_mfma_f32_16x16x32_bf16 v[126:129], v[166:169], v[100:103], v[126:129]
	v_mfma_f32_16x16x32_bf16 v[122:125], v[166:169], v[76:79], v[122:125]
	ds_read_b128 v[162:165], v206 offset:256
	s_waitcnt lgkmcnt(2)
	v_mfma_f32_16x16x32_bf16 v[130:133], v[170:173], v[76:79], v[130:133]
	v_mfma_f32_16x16x32_bf16 v[134:137], v[170:173], v[100:103], v[134:137]
	ds_read_b128 v[166:169], v206 offset:6400
	s_waitcnt lgkmcnt(2)
	v_mfma_f32_16x16x32_bf16 v[142:145], v[174:177], v[100:103], v[142:145]
	v_mfma_f32_16x16x32_bf16 v[138:141], v[174:177], v[76:79], v[138:141]
	ds_read_b128 v[170:173], v206 offset:12544
	s_waitcnt lgkmcnt(2)
	v_mfma_f32_16x16x32_bf16 v[114:117], v[162:165], v[80:83], v[114:117]
	v_mfma_f32_16x16x32_bf16 v[118:121], v[162:165], v[104:107], v[118:121]
	ds_read_b128 v[174:177], v206 offset:18688
	s_waitcnt lgkmcnt(2)
	v_mfma_f32_16x16x32_bf16 v[126:129], v[166:169], v[104:107], v[126:129]
	v_mfma_f32_16x16x32_bf16 v[122:125], v[166:169], v[80:83], v[122:125]
	ds_read_b128 v[162:165], v207 offset:256
	s_waitcnt lgkmcnt(2)
	v_mfma_f32_16x16x32_bf16 v[130:133], v[170:173], v[80:83], v[130:133]
	v_mfma_f32_16x16x32_bf16 v[134:137], v[170:173], v[104:107], v[134:137]
	ds_read_b128 v[166:169], v207 offset:6400
	s_waitcnt lgkmcnt(2)
	v_mfma_f32_16x16x32_bf16 v[142:145], v[174:177], v[104:107], v[142:145]
	v_mfma_f32_16x16x32_bf16 v[138:141], v[174:177], v[80:83], v[138:141]
	ds_read_b128 v[170:173], v207 offset:12544
	s_waitcnt lgkmcnt(2)
	v_mfma_f32_16x16x32_bf16 v[114:117], v[162:165], v[84:87], v[114:117]
	v_mfma_f32_16x16x32_bf16 v[118:121], v[162:165], v[108:111], v[118:121]
	ds_read_b128 v[174:177], v207 offset:18688
	s_waitcnt lgkmcnt(2)
	v_mfma_f32_16x16x32_bf16 v[126:129], v[166:169], v[108:111], v[126:129]
	v_mfma_f32_16x16x32_bf16 v[122:125], v[166:169], v[84:87], v[122:125]
	s_waitcnt lgkmcnt(1)
	v_mfma_f32_16x16x32_bf16 v[130:133], v[170:173], v[84:87], v[130:133]
	v_mfma_f32_16x16x32_bf16 v[134:137], v[170:173], v[108:111], v[134:137]
	s_waitcnt lgkmcnt(0)
	v_mfma_f32_16x16x32_bf16 v[142:145], v[174:177], v[108:111], v[142:145]
	v_mfma_f32_16x16x32_bf16 v[138:141], v[174:177], v[84:87], v[138:141]
	ds_read_b64_tr_b16 v[162:163], v208 offset:32768
	ds_read_b64_tr_b16 v[164:165], v208 offset:36864
	ds_read_b64_tr_b16 v[166:167], v209 offset:32768
	ds_read_b64_tr_b16 v[168:169], v209 offset:36864
	ds_read_b64_tr_b16 v[170:171], v210 offset:32768
	ds_read_b64_tr_b16 v[172:173], v210 offset:36864
	s_nop 7
	v_max3_f32 v232, v114, v115, v116
	v_max_f32_e32 v232, v232, v117
	v_max3_f32 v233, v118, v119, v120
	v_max_f32_e32 v233, v233, v121
	v_max3_f32 v232, v232, v122, v123
	v_max3_f32 v232, v232, v124, v125
	v_max3_f32 v233, v233, v126, v127
	v_max3_f32 v233, v233, v128, v129
	v_max3_f32 v232, v232, v130, v131
	v_max3_f32 v232, v232, v132, v133
	v_max3_f32 v233, v233, v134, v135
	v_max3_f32 v233, v233, v136, v137
	v_max3_f32 v232, v232, v138, v139
	v_max3_f32 v232, v232, v140, v141
	v_max3_f32 v233, v233, v142, v143
	v_max3_f32 v233, v233, v144, v145
	v_max_f32_e32 v234, v232, v233
	v_cmp_ge_f32_e32 vcc, s38, v234
	s_cmp_eq_u64 vcc, exec
	s_cbranch_scc0 .Lat_rare_2
; #define SBAR() __builtin_amdgcn_sched_barrier(0)
; __device__ __forceinline__ void finishSM(f32x16& p0, f32x16& p1, float alpha, float& l_reg, bf16x8& pa0, bf16x8& pa1, bf16x8& pa2, bf16x8& pa3) {
; #pragma unroll
;   for (int r = 0; r < 16; ++r) p1[r] = __builtin_amdgcn_exp2f(p1[r]);
;   float ps = 0;
; #pragma unroll
;   for (int r = 0; r < 16; ++r) ps += p0[r];
; #pragma unroll
;   for (int r = 0; r < 16; ++r) ps += p1[r];
;   { auto rr = __builtin_amdgcn_permlane32_swap(__float_as_uint(ps), __float_as_uint(ps), false, false);
;     ps = __uint_as_float(rr[0]) + __uint_as_float(rr[1]); }
;   l_reg = l_reg * alpha + ps;
;     ...
;   PK4(p0, 0, pa0); PK4(p0, 8, pa1); PK4(p1, 0, pa2); PK4(p1, 8, pa3);
;     ...
; }
; template <int D0> __device__ __forceinline__ void pv_one(f32x16& od, int vb, bf16x8 pa0, bf16x8 pa1, bf16x8 pa2, bf16x8 pa3) {
;   const s16x4 l0 = tr_read<v_rd_off(D0, 0, 0)>(vb), h0 = tr_read<v_rd_off(D0, 0, 1)>(vb), l1 = tr_read<v_rd_off(D0, 1, 0)>(vb), h1 = tr_read<v_rd_off(D0, 1, 1)>(vb);
;   const s16x4 l2 = tr_read<v_rd_off(D0, 2, 0)>(vb), h2 = tr_read<v_rd_off(D0, 2, 1)>(vb), l3 = tr_read<v_rd_off(D0, 3, 0)>(vb), h3 = tr_read<v_rd_off(D0, 3, 1)>(vb);
;   asm volatile("s_waitcnt lgkmcnt(0)" ::: "memory"); SBAR();
;     ...
;   od = __builtin_amdgcn_mfma_f32_32x32x16_bf16(pa0, PK(l0, h0), od, 0, 0, 0);
;   od = __builtin_amdgcn_mfma_f32_32x32x16_bf16(pa1, PK(l1, h1), od, 0, 0, 0);
;   od = __builtin_amdgcn_mfma_f32_32x32x16_bf16(pa2, PK(l2, h2), od, 0, 0, 0);
;   od = __builtin_amdgcn_mfma_f32_32x32x16_bf16(pa3, PK(l3, h3), od, 0, 0, 0);
;     ...
; }
; __device__ __forceinline__ void pv_d0(f32x16* o, int vb, bf16x8 pa0, bf16x8 pa1, bf16x8 pa2, bf16x8 pa3) {
;   pv_one<0>(o[0], vb, pa0, pa1, pa2, pa3); pv_one<1>(o[1], vb, pa0, pa1, pa2, pa3); pv_one<2>(o[2], vb, pa0, pa1, pa2, pa3); pv_one<3>(o[3], vb, pa0, pa1, pa2, pa3);
.Lat_cont_2:
	v_exp_f32_e32 v114, v114
	v_exp_f32_e32 v115, v115
	v_exp_f32_e32 v116, v116
	v_exp_f32_e32 v117, v117
	v_add_f32_e32 v220, v220, v114
	v_add_f32_e32 v220, v220, v115
	v_add_f32_e32 v220, v220, v116
	v_add_f32_e32 v220, v220, v117
	v_exp_f32_e32 v122, v122
	v_exp_f32_e32 v123, v123
	v_exp_f32_e32 v124, v124
	v_exp_f32_e32 v125, v125
	v_add_f32_e32 v220, v220, v122
	v_add_f32_e32 v220, v220, v123
	v_add_f32_e32 v220, v220, v124
	v_add_f32_e32 v220, v220, v125
	v_cvt_pk_bf16_f32 v146, v114, v115
	v_cvt_pk_bf16_f32 v147, v116, v117
	v_cvt_pk_bf16_f32 v148, v122, v123
	v_cvt_pk_bf16_f32 v149, v124, v125
	v_exp_f32_e32 v118, v118
	v_exp_f32_e32 v119, v119
	v_exp_f32_e32 v120, v120
	v_exp_f32_e32 v121, v121
	v_add_f32_e32 v221, v221, v118
	v_add_f32_e32 v221, v221, v119
	v_add_f32_e32 v221, v221, v120
	v_add_f32_e32 v221, v221, v121
	v_exp_f32_e32 v126, v126
	v_exp_f32_e32 v127, v127
	v_exp_f32_e32 v128, v128
	v_exp_f32_e32 v129, v129
	v_add_f32_e32 v221, v221, v126
	v_add_f32_e32 v221, v221, v127
	v_add_f32_e32 v221, v221, v128
	v_add_f32_e32 v221, v221, v129
	v_cvt_pk_bf16_f32 v154, v118, v119
	v_cvt_pk_bf16_f32 v155, v120, v121
	v_cvt_pk_bf16_f32 v156, v126, v127
	v_cvt_pk_bf16_f32 v157, v128, v129
	s_nop 1
	s_waitcnt lgkmcnt(4)
	v_mfma_f32_16x16x32_bf16 v[0:3], v[146:149], v[162:165], v[0:3]
	v_mfma_f32_16x16x32_bf16 v[32:35], v[154:157], v[162:165], v[32:35]
	ds_read_b64_tr_b16 v[174:175], v211 offset:32768
	ds_read_b64_tr_b16 v[176:177], v211 offset:36864
	v_exp_f32_e32 v130, v130
	v_exp_f32_e32 v131, v131
	v_exp_f32_e32 v132, v132
	v_exp_f32_e32 v133, v133
	v_add_f32_e32 v220, v220, v130
	s_waitcnt lgkmcnt(4)
	v_mfma_f32_16x16x32_bf16 v[36:39], v[154:157], v[166:169], v[36:39]
	v_mfma_f32_16x16x32_bf16 v[4:7], v[146:149], v[166:169], v[4:7]
	ds_read_b64_tr_b16 v[162:163], v212 offset:32768
	ds_read_b64_tr_b16 v[164:165], v212 offset:36864
	v_add_f32_e32 v220, v220, v131
	v_add_f32_e32 v220, v220, v132
	v_add_f32_e32 v220, v220, v133
	v_exp_f32_e32 v138, v138
	v_exp_f32_e32 v139, v139
	s_waitcnt lgkmcnt(4)
	v_mfma_f32_16x16x32_bf16 v[8:11], v[146:149], v[170:173], v[8:11]
	v_mfma_f32_16x16x32_bf16 v[40:43], v[154:157], v[170:173], v[40:43]
	ds_read_b64_tr_b16 v[166:167], v213 offset:32768
	ds_read_b64_tr_b16 v[168:169], v213 offset:36864
	v_exp_f32_e32 v140, v140
	v_exp_f32_e32 v141, v141
	v_add_f32_e32 v220, v220, v138
	v_add_f32_e32 v220, v220, v139
	v_add_f32_e32 v220, v220, v140
	s_waitcnt lgkmcnt(4)
	v_mfma_f32_16x16x32_bf16 v[44:47], v[154:157], v[174:177], v[44:47]
	v_mfma_f32_16x16x32_bf16 v[12:15], v[146:149], v[174:177], v[12:15]
	ds_read_b64_tr_b16 v[170:171], v214 offset:32768
	ds_read_b64_tr_b16 v[172:173], v214 offset:36864
	v_add_f32_e32 v220, v220, v141
	v_cvt_pk_bf16_f32 v150, v130, v131
	v_cvt_pk_bf16_f32 v151, v132, v133
	v_cvt_pk_bf16_f32 v152, v138, v139
	v_cvt_pk_bf16_f32 v153, v140, v141
	s_waitcnt lgkmcnt(4)
	v_mfma_f32_16x16x32_bf16 v[16:19], v[146:149], v[162:165], v[16:19]
	v_mfma_f32_16x16x32_bf16 v[48:51], v[154:157], v[162:165], v[48:51]
	ds_read_b64_tr_b16 v[174:175], v215 offset:32768
	ds_read_b64_tr_b16 v[176:177], v215 offset:36864
	v_exp_f32_e32 v134, v134
	v_exp_f32_e32 v135, v135
	v_exp_f32_e32 v136, v136
	v_exp_f32_e32 v137, v137
	v_add_f32_e32 v221, v221, v134
	s_waitcnt lgkmcnt(4)
	v_mfma_f32_16x16x32_bf16 v[52:55], v[154:157], v[166:169], v[52:55]
	v_mfma_f32_16x16x32_bf16 v[20:23], v[146:149], v[166:169], v[20:23]
	ds_read_b64_tr_b16 v[162:163], v208 offset:40960
	ds_read_b64_tr_b16 v[164:165], v208 offset:45056
	v_add_f32_e32 v221, v221, v135
	v_add_f32_e32 v221, v221, v136
	v_add_f32_e32 v221, v221, v137
	v_exp_f32_e32 v142, v142
	v_exp_f32_e32 v143, v143
	s_waitcnt lgkmcnt(4)
	v_mfma_f32_16x16x32_bf16 v[24:27], v[146:149], v[170:173], v[24:27]
	v_mfma_f32_16x16x32_bf16 v[56:59], v[154:157], v[170:173], v[56:59]
	ds_read_b64_tr_b16 v[166:167], v209 offset:40960
	ds_read_b64_tr_b16 v[168:169], v209 offset:45056
	v_exp_f32_e32 v144, v144
	v_exp_f32_e32 v145, v145
	v_add_f32_e32 v221, v221, v142
	v_add_f32_e32 v221, v221, v143
	v_add_f32_e32 v221, v221, v144
	s_waitcnt lgkmcnt(4)
	v_mfma_f32_16x16x32_bf16 v[60:63], v[154:157], v[174:177], v[60:63]
	v_mfma_f32_16x16x32_bf16 v[28:31], v[146:149], v[174:177], v[28:31]
	ds_read_b64_tr_b16 v[170:171], v210 offset:40960
	ds_read_b64_tr_b16 v[172:173], v210 offset:45056
	v_add_f32_e32 v221, v221, v145
	v_cvt_pk_bf16_f32 v158, v134, v135
	v_cvt_pk_bf16_f32 v159, v136, v137
	v_cvt_pk_bf16_f32 v160, v142, v143
	v_cvt_pk_bf16_f32 v161, v144, v145
	s_waitcnt lgkmcnt(4)
	s_nop 1
	v_mfma_f32_16x16x32_bf16 v[0:3], v[150:153], v[162:165], v[0:3]
	v_mfma_f32_16x16x32_bf16 v[32:35], v[158:161], v[162:165], v[32:35]
	ds_read_b64_tr_b16 v[174:175], v211 offset:40960
	ds_read_b64_tr_b16 v[176:177], v211 offset:45056
	s_waitcnt lgkmcnt(4)
	v_mfma_f32_16x16x32_bf16 v[36:39], v[158:161], v[166:169], v[36:39]
	v_mfma_f32_16x16x32_bf16 v[4:7], v[150:153], v[166:169], v[4:7]
	ds_read_b64_tr_b16 v[162:163], v212 offset:40960
	ds_read_b64_tr_b16 v[164:165], v212 offset:45056
	s_waitcnt lgkmcnt(4)
	v_mfma_f32_16x16x32_bf16 v[8:11], v[150:153], v[170:173], v[8:11]
	v_mfma_f32_16x16x32_bf16 v[40:43], v[158:161], v[170:173], v[40:43]
	ds_read_b64_tr_b16 v[166:167], v213 offset:40960
	ds_read_b64_tr_b16 v[168:169], v213 offset:45056
	s_waitcnt lgkmcnt(4)
	v_mfma_f32_16x16x32_bf16 v[44:47], v[158:161], v[174:177], v[44:47]
	v_mfma_f32_16x16x32_bf16 v[12:15], v[150:153], v[174:177], v[12:15]
	ds_read_b64_tr_b16 v[170:171], v214 offset:40960
	ds_read_b64_tr_b16 v[172:173], v214 offset:45056
	s_waitcnt lgkmcnt(4)
	v_mfma_f32_16x16x32_bf16 v[16:19], v[150:153], v[162:165], v[16:19]
	v_mfma_f32_16x16x32_bf16 v[48:51], v[158:161], v[162:165], v[48:51]
	ds_read_b64_tr_b16 v[174:175], v215 offset:40960
	ds_read_b64_tr_b16 v[176:177], v215 offset:45056
	s_waitcnt lgkmcnt(4)
	v_mfma_f32_16x16x32_bf16 v[52:55], v[158:161], v[166:169], v[52:55]
	v_mfma_f32_16x16x32_bf16 v[20:23], v[150:153], v[166:169], v[20:23]
	s_waitcnt lgkmcnt(2)
	v_mfma_f32_16x16x32_bf16 v[24:27], v[150:153], v[170:173], v[24:27]
	v_mfma_f32_16x16x32_bf16 v[56:59], v[158:161], v[170:173], v[56:59]
	s_waitcnt lgkmcnt(0)
	v_mfma_f32_16x16x32_bf16 v[60:63], v[158:161], v[174:177], v[60:63]
	v_mfma_f32_16x16x32_bf16 v[28:31], v[150:153], v[174:177], v[28:31]
	s_waitcnt vmcnt(5)
	s_barrier
; template <bool FIRST>
; __device__ __forceinline__ void partialSM(f32x16& p0, f32x16& p1, float& m_reg, float& alpha) {
;   constexpr float THR2 = THR * 1.4426950408889634f;
;   float pmax = p0[0];
; #pragma unroll
;   for (int r = 1; r < 16; ++r) pmax = fmaxf(pmax, p0[r]);
; #pragma unroll
;   for (int r = 0; r < 16; ++r) pmax = fmaxf(pmax, p1[r]);
;   { auto rr = __builtin_amdgcn_permlane32_swap(__float_as_uint(pmax), __float_as_uint(pmax), false, false);
;     pmax = fmaxf(__uint_as_float(rr[0]), __uint_as_float(rr[1])); }
;   if (!FIRST && __builtin_expect(__all(pmax <= THR2), 1)) { alpha = 1.f; }
; __device__ __forceinline__ void qkt(f32x16& p0, f32x16& p1, const char* Ks, const bf16x8* qr, const char* qL, int r32, int hi, float negm) {
; #pragma unroll
;   for (int r = 0; r < 16; ++r) { p0[r] = negm; p1[r] = negm; }
; #pragma unroll
;   for (int d0 = 0; d0 < 12; ++d0) { int cb = (d0 * 16 + hi * 8) * 2;
;     bf16x8 b0 = *reinterpret_cast<const bf16x8*>(Ks + KSWZ(r32, cb));
;     bf16x8 b1 = *reinterpret_cast<const bf16x8*>(Ks + KSWZ(32 + r32, cb));
;     const bf16x8 q = d0 < 8 ? qr[d0 < 8 ? d0 : 0] : *reinterpret_cast<const bf16x8*>(qL + (d0 - 8) * 1024);
;     p0 = __builtin_amdgcn_mfma_f32_32x32x16_bf16(b0, q, p0, 0, 0, 0);
;     p1 = __builtin_amdgcn_mfma_f32_32x32x16_bf16(b1, q, p1, 0, 0, 0); }
; }
	s_add_i32 m0, s43, 98304
	s_nop 0
	global_load_lds_dwordx4 v178, s[24:25]
	s_add_i32 m0, s43, 106496
	s_nop 0
	global_load_lds_dwordx4 v180, s[24:25]
	s_add_i32 m0, s43, 114688
	s_nop 0
	global_load_lds_dwordx4 v182, s[24:25]
	s_add_i32 m0, s43, 32768
	s_nop 0
	global_load_lds_dwordx4 v184, s[26:27]
	s_add_i32 m0, s43, 40960
	s_nop 0
	global_load_lds_dwordx4 v186, s[26:27]
	v_add_u32_e32 v178, v188, v178
	v_add_u32_e32 v180, v190, v180
	v_add_u32_e32 v182, v192, v182
	s_add_u32 s26, s26, 0x4000
	s_addc_u32 s27, s27, 0
	ds_read_b128 v[162:165], v202 offset:0
	ds_read_b128 v[166:169], v202 offset:6144
	ds_read_b128 v[170:173], v202 offset:12288
	s_waitcnt lgkmcnt(2)
	v_mfma_f32_16x16x32_bf16 v[114:117], v[162:165], v[64:67], v[224:227]
	v_mfma_f32_16x16x32_bf16 v[118:121], v[162:165], v[88:91], v[228:231]
	ds_read_b128 v[174:177], v202 offset:18432
	s_waitcnt lgkmcnt(2)
	v_mfma_f32_16x16x32_bf16 v[126:129], v[166:169], v[88:91], v[228:231]
	v_mfma_f32_16x16x32_bf16 v[122:125], v[166:169], v[64:67], v[224:227]
	ds_read_b128 v[162:165], v203 offset:0
	s_waitcnt lgkmcnt(2)
	v_mfma_f32_16x16x32_bf16 v[130:133], v[170:173], v[64:67], v[224:227]
	v_mfma_f32_16x16x32_bf16 v[134:137], v[170:173], v[88:91], v[228:231]
	ds_read_b128 v[166:169], v203 offset:6144
	s_waitcnt lgkmcnt(2)
	v_mfma_f32_16x16x32_bf16 v[142:145], v[174:177], v[88:91], v[228:231]
	v_mfma_f32_16x16x32_bf16 v[138:141], v[174:177], v[64:67], v[224:227]
	ds_read_b128 v[170:173], v203 offset:12288
	s_waitcnt lgkmcnt(2)
	v_mfma_f32_16x16x32_bf16 v[114:117], v[162:165], v[68:71], v[114:117]
	v_mfma_f32_16x16x32_bf16 v[118:121], v[162:165], v[92:95], v[118:121]
	ds_read_b128 v[174:177], v203 offset:18432
	s_waitcnt lgkmcnt(2)
	v_mfma_f32_16x16x32_bf16 v[126:129], v[166:169], v[92:95], v[126:129]
	v_mfma_f32_16x16x32_bf16 v[122:125], v[166:169], v[68:71], v[122:125]
	ds_read_b128 v[162:165], v202 offset:128
	s_waitcnt lgkmcnt(2)
	v_mfma_f32_16x16x32_bf16 v[130:133], v[170:173], v[68:71], v[130:133]
	v_mfma_f32_16x16x32_bf16 v[134:137], v[170:173], v[92:95], v[134:137]
	ds_read_b128 v[166:169], v202 offset:6272
	s_waitcnt lgkmcnt(2)
	v_mfma_f32_16x16x32_bf16 v[142:145], v[174:177], v[92:95], v[142:145]
	v_mfma_f32_16x16x32_bf16 v[138:141], v[174:177], v[68:71], v[138:141]
	ds_read_b128 v[170:173], v202 offset:12416
	s_waitcnt lgkmcnt(2)
	v_mfma_f32_16x16x32_bf16 v[114:117], v[162:165], v[72:75], v[114:117]
	v_mfma_f32_16x16x32_bf16 v[118:121], v[162:165], v[96:99], v[118:121]
	ds_read_b128 v[174:177], v202 offset:18560
	s_waitcnt lgkmcnt(2)
	v_mfma_f32_16x16x32_bf16 v[126:129], v[166:169], v[96:99], v[126:129]
	v_mfma_f32_16x16x32_bf16 v[122:125], v[166:169], v[72:75], v[122:125]
	ds_read_b128 v[162:165], v203 offset:128
	s_waitcnt lgkmcnt(2)
	v_mfma_f32_16x16x32_bf16 v[130:133], v[170:173], v[72:75], v[130:133]
	v_mfma_f32_16x16x32_bf16 v[134:137], v[170:173], v[96:99], v[134:137]
	ds_read_b128 v[166:169], v203 offset:6272
	s_waitcnt lgkmcnt(2)
	v_mfma_f32_16x16x32_bf16 v[142:145], v[174:177], v[96:99], v[142:145]
	v_mfma_f32_16x16x32_bf16 v[138:141], v[174:177], v[72:75], v[138:141]
	ds_read_b128 v[170:173], v203 offset:12416
	s_waitcnt lgkmcnt(2)
	v_mfma_f32_16x16x32_bf16 v[114:117], v[162:165], v[76:79], v[114:117]
	v_mfma_f32_16x16x32_bf16 v[118:121], v[162:165], v[100:103], v[118:121]
	ds_read_b128 v[174:177], v203 offset:18560
	s_waitcnt lgkmcnt(2)
	v_mfma_f32_16x16x32_bf16 v[126:129], v[166:169], v[100:103], v[126:129]
	v_mfma_f32_16x16x32_bf16 v[122:125], v[166:169], v[76:79], v[122:125]
	ds_read_b128 v[162:165], v202 offset:256
	s_waitcnt lgkmcnt(2)
	v_mfma_f32_16x16x32_bf16 v[130:133], v[170:173], v[76:79], v[130:133]
	v_mfma_f32_16x16x32_bf16 v[134:137], v[170:173], v[100:103], v[134:137]
	ds_read_b128 v[166:169], v202 offset:6400
	s_waitcnt lgkmcnt(2)
	v_mfma_f32_16x16x32_bf16 v[142:145], v[174:177], v[100:103], v[142:145]
	v_mfma_f32_16x16x32_bf16 v[138:141], v[174:177], v[76:79], v[138:141]
	ds_read_b128 v[170:173], v202 offset:12544
	s_waitcnt lgkmcnt(2)
	v_mfma_f32_16x16x32_bf16 v[114:117], v[162:165], v[80:83], v[114:117]
	v_mfma_f32_16x16x32_bf16 v[118:121], v[162:165], v[104:107], v[118:121]
	ds_read_b128 v[174:177], v202 offset:18688
	s_waitcnt lgkmcnt(2)
	v_mfma_f32_16x16x32_bf16 v[126:129], v[166:169], v[104:107], v[126:129]
	v_mfma_f32_16x16x32_bf16 v[122:125], v[166:169], v[80:83], v[122:125]
	ds_read_b128 v[162:165], v203 offset:256
	s_waitcnt lgkmcnt(2)
	v_mfma_f32_16x16x32_bf16 v[130:133], v[170:173], v[80:83], v[130:133]
	v_mfma_f32_16x16x32_bf16 v[134:137], v[170:173], v[104:107], v[134:137]
	ds_read_b128 v[166:169], v203 offset:6400
	s_waitcnt lgkmcnt(2)
	v_mfma_f32_16x16x32_bf16 v[142:145], v[174:177], v[104:107], v[142:145]
	v_mfma_f32_16x16x32_bf16 v[138:141], v[174:177], v[80:83], v[138:141]
	ds_read_b128 v[170:173], v203 offset:12544
	s_waitcnt lgkmcnt(2)
	v_mfma_f32_16x16x32_bf16 v[114:117], v[162:165], v[84:87], v[114:117]
	v_mfma_f32_16x16x32_bf16 v[118:121], v[162:165], v[108:111], v[118:121]
	ds_read_b128 v[174:177], v203 offset:18688
	s_waitcnt lgkmcnt(2)
	v_mfma_f32_16x16x32_bf16 v[126:129], v[166:169], v[108:111], v[126:129]
	v_mfma_f32_16x16x32_bf16 v[122:125], v[166:169], v[84:87], v[122:125]
	s_waitcnt lgkmcnt(1)
	v_mfma_f32_16x16x32_bf16 v[130:133], v[170:173], v[84:87], v[130:133]
	v_mfma_f32_16x16x32_bf16 v[134:137], v[170:173], v[108:111], v[134:137]
	s_waitcnt lgkmcnt(0)
	v_mfma_f32_16x16x32_bf16 v[142:145], v[174:177], v[108:111], v[142:145]
	v_mfma_f32_16x16x32_bf16 v[138:141], v[174:177], v[84:87], v[138:141]
	ds_read_b64_tr_b16 v[162:163], v208 offset:0
	ds_read_b64_tr_b16 v[164:165], v208 offset:4096
	ds_read_b64_tr_b16 v[166:167], v209 offset:0
	ds_read_b64_tr_b16 v[168:169], v209 offset:4096
	ds_read_b64_tr_b16 v[170:171], v210 offset:0
	ds_read_b64_tr_b16 v[172:173], v210 offset:4096
	s_nop 7
	v_max3_f32 v232, v114, v115, v116
	v_max_f32_e32 v232, v232, v117
	v_max3_f32 v233, v118, v119, v120
	v_max_f32_e32 v233, v233, v121
	v_max3_f32 v232, v232, v122, v123
	v_max3_f32 v232, v232, v124, v125
	v_max3_f32 v233, v233, v126, v127
	v_max3_f32 v233, v233, v128, v129
	v_max3_f32 v232, v232, v130, v131
	v_max3_f32 v232, v232, v132, v133
	v_max3_f32 v233, v233, v134, v135
	v_max3_f32 v233, v233, v136, v137
	v_max3_f32 v232, v232, v138, v139
	v_max3_f32 v232, v232, v140, v141
	v_max3_f32 v233, v233, v142, v143
	v_max3_f32 v233, v233, v144, v145
	v_max_f32_e32 v234, v232, v233
	v_cmp_ge_f32_e32 vcc, s38, v234
	s_cmp_eq_u64 vcc, exec
	s_cbranch_scc0 .Lat_rare_3
